# M0 save/restore removed around the 60 inline-asm LDS-DMA blocks (on v34)
# speedup vs baseline: 1.0120x; 1.0120x over previous
; #define DMA_K(t, slot) do { const bf16_t* s_ = Knp + (long)(t) * (KVBLK * LDK); const unsigned d_ = (unsigned)__builtin_amdgcn_readfirstlane(kn_dst + (slot) * SHM_KN); \
;     glds16s(s_, kn_off, d_); glds16s(s_ + 16 * LDK, kn_off, d_ + 4096); glds16s(Krp + (long)(t) * (KVBLK * 64), kr_off, (unsigned)__builtin_amdgcn_readfirstlane(kr_dst + (slot) * SHM_KR)); } while (0)
; #define DMA_V(t, slot) do { const bf16_t* s_ = Vp + (long)(t) * (KVBLK * LDK); const unsigned d_ = (unsigned)__builtin_amdgcn_readfirstlane(v_dst + (slot) * SHM_V); \
;     glds16s(s_, v_off, d_); glds16s(s_ + 32 * LDK, v_off, d_ + 8192); } while (0)
; __device__ __forceinline__ void mla_unit(char* lds, const bf16_t* __restrict__ Qp, const bf16_t* __restrict__ Knp, const bf16_t* __restrict__ Vp, ...
;     ...
;   const int pk = (wid & 3) + 8 * (wid >> 2);
;   const int krow_n = 4 * pk + (lane >> 4);
;   const unsigned kn_off = (unsigned)(krow_n * LDK + (((lane & 15) ^ (krow_n & 15)) << 3)) * 2u;
;   const int krow_r = 8 * wid + (lane >> 3);
;   const unsigned kr_off = (unsigned)(krow_r * 64 + (((lane & 7) ^ ((krow_r >> 1) & 7)) << 3)) * 2u;
;   const int vst_ = 2 * wid + (lane >> 5), vkk = (vst_ >> 2) * 8 + ((lane >> 2) & 7), vkey = (vkk & ~0xC) | ((vkk & 4) << 1) | ((vkk & 8) >> 1), vcol = (vst_ & 3) * 32 + (lane & 3) * 8;
;   const unsigned v_off = (unsigned)(vkey * LDK + vcol) * 2u;
;   const unsigned kn_dst = lds0 + P_KN + pk * 1024, kr_dst = lds0 + P_KR + wid * 1024, v_dst = lds0 + P_V + wid * 1024;
;     ...
;   if (first) { DMA_K(0, 0); DMA_V(0, 0); DMA_K(1, 1); DMA_V(1, 1); DMA_K(2, 2); }
.Lmla_prio_skip:
	s_ashr_i32 s5, s0, 5
	s_and_b32 s1, s8, 3
	s_and_b32 s5, s5, -8
	s_or_b32 s1, s1, s5
	s_lshl_b32 s5, s1, 2
	s_ashr_i32 s12, s0, 4
	v_bfe_u32 v1, v50, 4, 2
	s_ashr_i32 s7, s6, 31
	s_and_b32 s13, s12, 0x7ffff0
	s_lshr_b32 s12, s12, 1
	v_or_b32_e32 v2, s5, v1
	v_bitop3_b32 v1, s5, v50, v1 bitop3:0x36
	s_bfe_u32 s38, s74, 0x40005
	s_lshl_b64 s[30:31], s[6:7], 22
	s_lshl_b64 s[36:37], s[6:7], 20
	s_lshl_b32 s9, s8, 1
	s_and_b32 s12, s12, 4
	s_lshl_b32 s72, s1, 10
	v_lshlrev_b32_e32 v2, 9, v2
	v_lshlrev_b32_e32 v1, 4, v1
	s_cmp_lg_u32 0, -1
	v_and_or_b32 v197, v1, s53, v2
	v_bfe_u32 v1, v50, 3, 3
	s_cselect_b32 s1, 0, 0
	s_lshl_b32 s71, s8, 10
	v_lshl_or_b32 v1, s8, 3, v1
	s_add_i32 s14, s1, s72
	s_add_i32 s73, s71, s1
	v_lshlrev_b32_e32 v2, 7, v1
	v_lshrrev_b32_e32 v1, 1, v1
	s_add_i32 s76, s14, 0xc000
	s_add_i32 s75, s73, 0x18000
	v_readlane_b32 s1, v253, 3
	v_xor_b32_e32 v1, v1, v50
	s_cmp_lg_u32 s74, s1
	v_lshlrev_b32_e32 v1, 4, v1
	s_movk_i32 s1, 0x70
	v_and_or_b32 v198, v1, s1, v2
	v_lshrrev_b32_e32 v1, 2, v50
	v_lshrrev_b32_e32 v2, 1, v50
	v_bfe_u32 v49, v50, 5, 1
	v_and_or_b32 v1, v1, 3, s13
	v_and_b32_e32 v2, 8, v2
	v_lshlrev_b32_e32 v48, 4, v50
	v_or3_b32 v1, v1, v2, s12
	v_and_or_b32 v2, s9, 2, v49
	v_and_b32_e32 v3, 48, v48
	v_lshl_or_b32 v2, v2, 6, v3
	v_lshl_or_b32 v199, v1, 9, v2
	s_cbranch_scc1 .LBB0_238
	s_lshl_b32 s1, s38, 23
	v_readlane_b32 s5, v254, 62
	s_add_u32 s1, s5, s1
	v_readlane_b32 s5, v254, 63
	s_addc_u32 s5, s5, 0
	s_add_u32 s12, s1, s30
	s_addc_u32 s13, s5, s31
	s_add_u32 s14, s12, 0x100
	s_addc_u32 s15, s13, 0
	s_add_u32 s16, s26, s36
	s_addc_u32 s17, s27, s37
	s_mov_b32 m0, s76
	s_nop 0
	global_load_lds_dwordx4 v197, s[12:13]
	s_add_u32 s18, s12, 0x2000
	s_addc_u32 s19, s13, 0
	s_add_i32 s1, s76, 0x1000
	s_mov_b32 m0, s1
	s_nop 0
	global_load_lds_dwordx4 v197, s[18:19]
	s_mov_b32 m0, s75
	s_nop 0
	global_load_lds_dwordx4 v198, s[16:17]
	s_nop 0
	s_mov_b32 m0, s73
	s_nop 0
	global_load_lds_dwordx4 v199, s[14:15]
	s_add_u32 s14, s12, 0x4100
	s_addc_u32 s15, s13, 0
	s_add_i32 s1, s73, 0x2000
	s_mov_b32 m0, s1
	s_nop 0
	global_load_lds_dwordx4 v199, s[14:15]
	s_add_u32 s14, s12, 0x8000
	s_addc_u32 s15, s13, 0
	s_cmp_lg_u32 0, -1
	s_cselect_b32 s1, 0, 0
	s_add_i32 s5, s1, s72
	s_add_i32 s9, s5, 0x10000
	s_mov_b32 m0, s9
	s_nop 0
	global_load_lds_dwordx4 v197, s[14:15]
	s_add_u32 s14, s12, 0xa000
	s_addc_u32 s15, s13, 0
	s_add_i32 s9, s5, 0x11000
	s_mov_b32 m0, s9
	s_nop 0
	global_load_lds_dwordx4 v197, s[14:15]
	s_add_u32 s14, s16, 0x2000
	s_addc_u32 s15, s17, 0
	s_add_i32 s1, s1, s71
	s_add_i32 s9, s1, 0x1a000
	s_mov_b32 m0, s9
	s_nop 0
	global_load_lds_dwordx4 v198, s[14:15]
	s_add_u32 s14, s12, 0x8100
	s_addc_u32 s15, s13, 0
	s_add_i32 s9, s1, 0x4000
	s_mov_b32 m0, s9
	s_nop 0
	global_load_lds_dwordx4 v199, s[14:15]
	s_add_u32 s14, s12, 0xc100
	s_addc_u32 s15, s13, 0
	s_add_i32 s9, s1, 0x6000
	s_mov_b32 m0, s9
	s_nop 0
	global_load_lds_dwordx4 v199, s[14:15]
	s_add_u32 s14, s12, 0x10000
	s_addc_u32 s15, s13, 0
	s_add_i32 s9, s5, 0x14000
	s_add_u32 s12, s12, 0x12000
	s_mov_b32 m0, s9
	s_nop 0
	global_load_lds_dwordx4 v197, s[14:15]
	s_addc_u32 s13, s13, 0
	s_add_i32 s5, s5, 0x15000
	s_mov_b32 m0, s5
	s_nop 0
	global_load_lds_dwordx4 v197, s[12:13]
	s_add_u32 s12, s16, 0x4000
	s_addc_u32 s13, s17, 0
	s_add_i32 s1, s1, 0x1c000
	s_mov_b32 m0, s1
	s_nop 0
	global_load_lds_dwordx4 v198, s[12:13]

.LBB0_241:
	s_waitcnt vmcnt(5) lgkmcnt(0)
	s_barrier
	s_mov_b32 s79, s70
	s_mov_b32 s70, s0
	s_lshl_b32 s13, s79, 14
	s_lshl_b32 s0, s79, 13
	s_lshl_b32 s1, s70, 14
	s_add_i32 s5, s13, 0
	v_add_u32_e32 v1, s5, v230
	v_add_u32_e32 v102, s5, v232
	ds_read_b128 v[98:101], v1 offset:49152
	ds_read_b128 v[236:239], v102 offset:57344
	v_add_u32_e32 v1, s5, v231
	v_add_u32_e32 v102, s5, v233
	ds_read_b128 v[240:243], v1 offset:49152
	ds_read_b128 v[244:247], v102 offset:57344
	s_waitcnt lgkmcnt(3)
	v_mfma_f32_32x32x16_bf16 v[114:129], v[98:101], v[130:133], v[66:81]
	v_add_u32_e32 v1, s5, v204
	v_add_u32_e32 v102, v1, v227
	ds_read_b128 v[248:251], v102 offset:49152
	v_add_u32_e32 v190, s1, v202
	v_add_u32_e32 v191, s0, v206
	v_exp_f32_e32 v192, v82
	ds_read_b128 v[210:213], v102 offset:57344
	s_waitcnt lgkmcnt(4)
	v_mfma_f32_32x32x16_bf16 v[98:113], v[236:239], v[130:133], v[66:81]
	v_add_f32_e32 v82, v192, v186
	v_exp_f32_e32 v193, v83
	s_waitcnt lgkmcnt(3)
	v_mfma_f32_32x32x16_bf16 v[114:129], v[240:243], v[134:137], v[114:129]
	v_add_u32_e32 v83, v1, v226
	ds_read_b128 v[186:189], v83 offset:49152
	v_add_f32_e32 v82, v193, v82
	v_exp_f32_e32 v235, v84
	s_waitcnt lgkmcnt(3)
	v_mfma_f32_32x32x16_bf16 v[98:113], v[244:247], v[134:137], v[98:113]
	ds_read_b128 v[236:239], v83 offset:57344
	v_add_f32_e32 v240, v235, v82
	v_exp_f32_e32 v220, v85
	s_waitcnt lgkmcnt(3)
	v_mfma_f32_32x32x16_bf16 v[114:129], v[248:251], v[138:141], v[114:129]
	v_add_u32_e32 v241, v1, v225
	ds_read_b128 v[82:85], v241 offset:49152
	v_exp_f32_e32 v244, v86
	v_add_f32_e32 v86, v220, v240
	s_waitcnt lgkmcnt(3)
	v_mfma_f32_32x32x16_bf16 v[98:113], v[210:213], v[138:141], v[98:113]
	ds_read_b128 v[240:243], v241 offset:57344
	v_add_f32_e32 v86, v244, v86
	v_exp_f32_e32 v245, v87
	s_waitcnt lgkmcnt(3)
	v_mfma_f32_32x32x16_bf16 v[114:129], v[186:189], v[142:145], v[114:129]
	v_add_u32_e32 v87, v1, v224
	ds_read_b128 v[210:213], v87 offset:49152
	v_add_f32_e32 v86, v245, v86
	v_exp_f32_e32 v246, v88
	s_waitcnt lgkmcnt(3)
	v_mfma_f32_32x32x16_bf16 v[98:113], v[236:239], v[142:145], v[98:113]
	ds_read_b128 v[186:189], v87 offset:57344
	v_add_f32_e32 v248, v246, v86
	v_exp_f32_e32 v247, v89
	s_waitcnt lgkmcnt(3)
	v_mfma_f32_32x32x16_bf16 v[114:129], v[82:85], v[154:157], v[114:129]
	v_add_u32_e32 v236, v1, v223
	ds_read_b128 v[86:89], v236 offset:49152
	v_add_f32_e32 v82, v247, v248
	v_exp_f32_e32 v249, v90
	s_waitcnt lgkmcnt(3)
	v_mfma_f32_32x32x16_bf16 v[98:113], v[240:243], v[154:157], v[98:113]
	ds_read_b128 v[236:239], v236 offset:57344
	v_add_f32_e32 v84, v249, v82
	v_exp_f32_e32 v248, v91
	v_cvt_pk_bf16_f32 v82, v192, v193
	v_cvt_pk_bf16_f32 v83, v235, v220
	s_waitcnt lgkmcnt(3)
	v_mfma_f32_32x32x16_bf16 v[114:129], v[210:213], v[150:153], v[114:129]
	v_add_u32_e32 v1, v1, v222
	ds_read_b128 v[240:243], v1 offset:49152
	v_add_f32_e32 v90, v248, v84
	v_exp_f32_e32 v192, v92
	v_cvt_pk_bf16_f32 v84, v244, v245
	v_cvt_pk_bf16_f32 v85, v246, v247
	s_waitcnt lgkmcnt(3)
	v_mfma_f32_32x32x16_bf16 v[98:113], v[186:189], v[150:153], v[98:113]
	ds_read_b128 v[210:213], v1 offset:57344
	v_exp_f32_e32 v1, v93
	v_add_f32_e32 v193, v192, v90
	v_permlane32_swap_b32_e32 v82, v84
	v_permlane32_swap_b32_e32 v83, v85
	s_waitcnt lgkmcnt(3)
	v_mfma_f32_32x32x16_bf16 v[114:129], v[86:89], v[146:149], v[114:129]
	v_add_u32_e32 v186, v191, v221
	ds_read_b128 v[90:93], v186
	v_exp_f32_e32 v220, v94
	v_add_f32_e32 v94, v1, v193
	s_waitcnt lgkmcnt(3)
	v_mfma_f32_32x32x16_bf16 v[98:113], v[236:239], v[146:149], v[98:113]
	ds_read_b128 v[86:89], v186 offset:4096
	v_add_f32_e32 v94, v220, v94
	v_exp_f32_e32 v193, v95
	s_waitcnt lgkmcnt(3)
	v_mfma_f32_32x32x16_bf16 v[114:129], v[240:243], v[158:161], v[114:129]
	v_add_u32_e32 v95, v191, v209
	ds_read_b128 v[186:189], v95
	v_add_f32_e32 v94, v193, v94
	v_exp_f32_e32 v235, v96
	s_waitcnt lgkmcnt(3)
	v_mfma_f32_32x32x16_bf16 v[98:113], v[210:213], v[158:161], v[98:113]
	ds_read_b128 v[236:239], v95 offset:4096
	v_add_f32_e32 v241, v235, v94
	v_exp_f32_e32 v240, v97
	s_waitcnt lgkmcnt(3)
	v_mfma_f32_32x32x16_bf16 v[114:129], v[90:93], v[162:165], v[114:129]
	v_add_u32_e32 v210, v191, v208
	ds_read_b128 v[94:97], v210
	v_add_f32_e32 v241, v240, v241
	s_waitcnt lgkmcnt(3)
	v_mfma_f32_32x32x16_bf16 v[98:113], v[86:89], v[162:165], v[98:113]
	ds_read_b128 v[90:93], v210 offset:4096
	v_cvt_pk_bf16_f32 v86, v249, v248
	v_cvt_pk_bf16_f32 v87, v192, v1
	s_waitcnt lgkmcnt(3)
	v_mfma_f32_32x32x16_bf16 v[114:129], v[186:189], v[166:169], v[114:129]
	v_add_u32_e32 v1, v191, v207
	ds_read_b128 v[210:213], v1
	v_cvt_pk_bf16_f32 v88, v220, v193
	v_cvt_pk_bf16_f32 v89, v235, v240
	s_waitcnt lgkmcnt(3)
	v_mfma_f32_32x32x16_bf16 v[98:113], v[236:239], v[166:169], v[98:113]
	ds_read_b128 v[186:189], v1 offset:4096
	v_permlane32_swap_b32_e32 v86, v88
	v_permlane32_swap_b32_e32 v87, v89
	s_waitcnt lgkmcnt(3)
	v_mfma_f32_32x32x16_bf16 v[114:129], v[94:97], v[170:173], v[114:129]
	v_mov_b32_e32 v1, v241
	s_nop 1
	v_permlane32_swap_b32_e32 v241, v1
	v_add_f32_e32 v1, v241, v1
	v_add_f32_e32 v1, v234, v1
	s_waitcnt lgkmcnt(2)
	v_mfma_f32_32x32x16_bf16 v[98:113], v[90:93], v[170:173], v[98:113]
	ds_read_b64_tr_b16 v[94:95], v190
	ds_read_b64_tr_b16 v[96:97], v190 offset:2048
	s_waitcnt lgkmcnt(3)
	v_mfma_f32_32x32x16_bf16 v[114:129], v[210:213], v[174:177], v[114:129]
	ds_read_b64_tr_b16 v[90:91], v190 offset:512
	ds_read_b64_tr_b16 v[92:93], v190 offset:2560
	s_waitcnt lgkmcnt(4)
	v_mfma_f32_32x32x16_bf16 v[98:113], v[186:189], v[174:177], v[98:113]
	ds_read_b64_tr_b16 v[210:211], v190 offset:1024
	ds_read_b64_tr_b16 v[212:213], v190 offset:3072
	s_add_u32 s18, s30, s46
	s_addc_u32 s19, s31, s47
	s_add_u32 s14, s18, 0x15000000
	s_addc_u32 s15, s19, 0
	s_waitcnt lgkmcnt(4)
	v_mfma_f32_32x32x16_bf16 v[50:65], v[182:185], v[94:97], v[50:65]
	s_add_u32 s6, s18, 0x15018000
	s_addc_u32 s7, s19, 0
	s_add_i32 s5, s1, s76
	s_add_u32 s8, s18, 0x15010100
	ds_read_b64_tr_b16 v[234:235], v190 offset:1536
	ds_read_b64_tr_b16 v[236:237], v190 offset:3584
	s_addc_u32 s9, s19, 0
	s_lshl_b32 s20, s77, 14
	s_add_i32 s12, s20, s73
	s_mov_b32 m0, s12
	s_nop 0
	global_load_lds_dwordx4 v199, s[8:9]
	s_waitcnt lgkmcnt(4)
	v_mfma_f32_32x32x16_bf16 v[34:49], v[182:185], v[90:93], v[34:49]
	ds_read_b64_tr_b16 v[94:95], v190 offset:4096
	ds_read_b64_tr_b16 v[96:97], v190 offset:6144
	s_add_u32 s8, s18, 0x15014100
	s_addc_u32 s9, s19, 0
	s_addk_i32 s12, 0x2000
	s_mov_b32 m0, s12
	s_nop 0
	global_load_lds_dwordx4 v199, s[8:9]
	s_waitcnt lgkmcnt(4)
	v_mfma_f32_32x32x16_bf16 v[18:33], v[182:185], v[210:213], v[18:33]
	ds_read_b64_tr_b16 v[186:187], v190 offset:4608
	ds_read_b64_tr_b16 v[188:189], v190 offset:6656
	s_mov_b32 m0, s5
	s_nop 0
	global_load_lds_dwordx4 v197, s[6:7]
	s_waitcnt lgkmcnt(4)
	v_mfma_f32_32x32x16_bf16 v[2:17], v[182:185], v[234:237], v[2:17]
	ds_read_b64_tr_b16 v[90:91], v190 offset:5120
	ds_read_b64_tr_b16 v[92:93], v190 offset:7168
	s_add_u32 s6, s18, 0x1501a000
	s_addc_u32 s7, s19, 0
	s_addk_i32 s5, 0x1000
	s_mov_b32 m0, s5
	s_nop 0
	global_load_lds_dwordx4 v197, s[6:7]
	v_max_f32_e32 v182, v115, v115
	v_max_f32_e32 v183, v114, v114
	v_max_f32_e32 v182, v183, v182
	v_max3_f32 v183, v116, v117, v99
	v_max3_f32 v182, v182, v98, v100
	v_max3_f32 v182, v182, v101, v118
	v_max3_f32 v183, v183, v120, v121
	v_max3_f32 v182, v182, v119, v102
	v_max3_f32 v183, v183, v104, v105
	v_max3_f32 v182, v182, v103, v122
	v_max3_f32 v183, v183, v124, v125
	v_max3_f32 v182, v182, v123, v106
	v_max3_f32 v183, v183, v108, v109
	v_max3_f32 v182, v182, v107, v126
	v_max3_f32 v183, v183, v128, v129
	v_max3_f32 v182, v182, v127, v110
	v_max3_f32 v183, v183, v112, v113
	v_max3_f32 v182, v182, v111, v183
	v_mov_b32_e32 v183, v182
	s_nop 1
	v_permlane32_swap_b32_e32 v182, v183
	v_max_f32_e32 v183, v183, v183
	v_max_f32_e32 v182, v182, v182
	v_max_f32_e32 v182, v182, v183
	v_cmp_lt_f32_e32 vcc, s92, v182
	s_cmp_lg_u64 vcc, 0
	s_cselect_b64 s[6:7], -1, 0
	s_cbranch_vccnz .LBB0_255
.LBB0_242:
	s_add_u32 s16, s36, s46
	s_addc_u32 s17, s37, s47
	s_add_u32 s8, s16, 0x6000
	s_addc_u32 s9, s17, 0
	s_lshl_b32 s5, s70, 13
	s_add_i32 s5, s5, s75
	s_waitcnt lgkmcnt(4)
	v_mfma_f32_32x32x16_bf16 v[50:65], v[178:181], v[94:97], v[50:65]
	ds_read_b64_tr_b16 v[182:183], v190 offset:5632
	ds_read_b64_tr_b16 v[184:185], v190 offset:7680
	s_mov_b32 m0, s5
	s_nop 0
	global_load_lds_dwordx4 v198, s[8:9]
	v_exp_f32_e32 v114, v114
	v_exp_f32_e32 v115, v115
	v_mov_b32_e32 v191, 0
	s_waitcnt lgkmcnt(4)
	v_mfma_f32_32x32x16_bf16 v[34:49], v[178:181], v[186:189], v[34:49]
	ds_read_b64_tr_b16 v[94:95], v190 offset:8192
	ds_read_b64_tr_b16 v[96:97], v190 offset:10240
	v_add_f32_e32 v186, v191, v114
	v_exp_f32_e32 v116, v116
	v_exp_f32_e32 v117, v117
	v_add_f32_e32 v191, v115, v186
	s_waitcnt lgkmcnt(4)
	v_mfma_f32_32x32x16_bf16 v[18:33], v[178:181], v[90:93], v[18:33]
	ds_read_b64_tr_b16 v[186:187], v190 offset:8704
	ds_read_b64_tr_b16 v[188:189], v190 offset:10752
	v_add_f32_e32 v90, v191, v116
	v_exp_f32_e32 v118, v118
	v_exp_f32_e32 v119, v119
	v_add_f32_e32 v191, v117, v90
	s_waitcnt lgkmcnt(4)
	v_mfma_f32_32x32x16_bf16 v[2:17], v[178:181], v[182:185], v[2:17]
	ds_read_b64_tr_b16 v[90:91], v190 offset:9216
	ds_read_b64_tr_b16 v[92:93], v190 offset:11264
	v_add_f32_e32 v178, v191, v118
	v_exp_f32_e32 v120, v120
	v_exp_f32_e32 v121, v121
	v_add_f32_e32 v182, v119, v178
	s_waitcnt lgkmcnt(4)
	v_mfma_f32_32x32x16_bf16 v[50:65], v[82:85], v[94:97], v[50:65]
	ds_read_b64_tr_b16 v[178:179], v190 offset:9728
	ds_read_b64_tr_b16 v[180:181], v190 offset:11776
	v_add_f32_e32 v94, v182, v120
	v_exp_f32_e32 v122, v122
	v_exp_f32_e32 v123, v123
	v_add_f32_e32 v184, v121, v94
	s_nop 0
	v_cvt_pk_bf16_f32 v182, v114, v115
	v_cvt_pk_bf16_f32 v183, v116, v117
	s_waitcnt lgkmcnt(4)
	v_mfma_f32_32x32x16_bf16 v[34:49], v[82:85], v[186:189], v[34:49]
	ds_read_b64_tr_b16 v[94:95], v190 offset:12288
	ds_read_b64_tr_b16 v[96:97], v190 offset:14336
	v_add_f32_e32 v184, v184, v122
	v_exp_f32_e32 v124, v124
	v_exp_f32_e32 v125, v125
	v_add_f32_e32 v191, v123, v184
	s_nop 0
	v_cvt_pk_bf16_f32 v184, v118, v119
	v_cvt_pk_bf16_f32 v185, v120, v121
	s_waitcnt lgkmcnt(4)
	v_mfma_f32_32x32x16_bf16 v[18:33], v[82:85], v[90:93], v[18:33]
	ds_read_b64_tr_b16 v[186:187], v190 offset:12800
	ds_read_b64_tr_b16 v[188:189], v190 offset:14848
	v_add_f32_e32 v90, v191, v124
	v_exp_f32_e32 v126, v126
	v_exp_f32_e32 v127, v127
	v_add_f32_e32 v191, v125, v90
	v_permlane32_swap_b32_e32 v182, v184
	v_permlane32_swap_b32_e32 v183, v185
	s_waitcnt lgkmcnt(4)
	v_mfma_f32_32x32x16_bf16 v[2:17], v[82:85], v[178:181], v[2:17]
	ds_read_b64_tr_b16 v[90:91], v190 offset:13312
	ds_read_b64_tr_b16 v[92:93], v190 offset:15360
	v_add_f32_e32 v82, v191, v126
	v_exp_f32_e32 v128, v128
	v_exp_f32_e32 v129, v129
	v_add_f32_e32 v82, v127, v82
	s_waitcnt lgkmcnt(4)
	v_mfma_f32_32x32x16_bf16 v[50:65], v[86:89], v[94:97], v[50:65]
	ds_read_b64_tr_b16 v[114:115], v190 offset:13824
	ds_read_b64_tr_b16 v[116:117], v190 offset:15872
	v_add_f32_e32 v82, v82, v128
	v_add_f32_e32 v82, v129, v82
	v_cvt_pk_bf16_f32 v178, v122, v123
	v_cvt_pk_bf16_f32 v179, v124, v125
	s_waitcnt lgkmcnt(4)
	v_mfma_f32_32x32x16_bf16 v[34:49], v[86:89], v[186:189], v[34:49]
	v_cvt_pk_bf16_f32 v180, v126, v127
	v_cvt_pk_bf16_f32 v181, v128, v129
	s_waitcnt lgkmcnt(2)
	v_mfma_f32_32x32x16_bf16 v[18:33], v[86:89], v[90:93], v[18:33]
	v_permlane32_swap_b32_e32 v178, v180
	v_permlane32_swap_b32_e32 v179, v181
	s_waitcnt lgkmcnt(0)
	v_mfma_f32_32x32x16_bf16 v[2:17], v[86:89], v[114:117], v[2:17]
	s_andn2_b64 vcc, exec, s[6:7]
	s_cbranch_vccnz .LBB0_244
	s_waitcnt lgkmcnt(0)
	v_add_u32_e32 v83, s33, v194
	ds_read_b128 v[84:87], v83 offset:224
	ds_read_b128 v[88:91], v83 offset:192
	ds_read_b128 v[92:95], v83 offset:160
	ds_read_b128 v[114:117], v83 offset:128
	s_waitcnt lgkmcnt(3)
	v_pk_mul_f32 v[62:63], v[62:63], v[84:85]
	s_waitcnt lgkmcnt(2)
	v_pk_mul_f32 v[58:59], v[58:59], v[88:89]
	s_waitcnt lgkmcnt(1)
	v_pk_mul_f32 v[54:55], v[54:55], v[92:93]
	v_pk_mul_f32 v[64:65], v[64:65], v[86:87]
	v_pk_mul_f32 v[60:61], v[60:61], v[90:91]
	v_pk_mul_f32 v[56:57], v[56:57], v[94:95]
	s_waitcnt lgkmcnt(0)
	v_pk_mul_f32 v[52:53], v[52:53], v[116:117]
	v_pk_mul_f32 v[50:51], v[50:51], v[114:115]
	v_pk_mul_f32 v[46:47], v[46:47], v[84:85]
	v_pk_mul_f32 v[42:43], v[42:43], v[88:89]
	v_pk_mul_f32 v[38:39], v[38:39], v[92:93]
	v_pk_mul_f32 v[48:49], v[48:49], v[86:87]
	v_pk_mul_f32 v[44:45], v[44:45], v[90:91]
	v_pk_mul_f32 v[40:41], v[40:41], v[94:95]
	v_pk_mul_f32 v[36:37], v[36:37], v[116:117]
	v_pk_mul_f32 v[34:35], v[34:35], v[114:115]
	v_pk_mul_f32 v[30:31], v[30:31], v[84:85]
	v_pk_mul_f32 v[26:27], v[26:27], v[88:89]
	v_pk_mul_f32 v[22:23], v[22:23], v[92:93]
	v_pk_mul_f32 v[32:33], v[32:33], v[86:87]
	v_pk_mul_f32 v[28:29], v[28:29], v[90:91]
	v_pk_mul_f32 v[24:25], v[24:25], v[94:95]
	v_pk_mul_f32 v[20:21], v[20:21], v[116:117]
	v_pk_mul_f32 v[18:19], v[18:19], v[114:115]
	v_pk_mul_f32 v[14:15], v[14:15], v[84:85]
	v_pk_mul_f32 v[10:11], v[10:11], v[88:89]
	v_pk_mul_f32 v[6:7], v[6:7], v[92:93]
	v_pk_mul_f32 v[16:17], v[16:17], v[86:87]
	v_pk_mul_f32 v[12:13], v[12:13], v[90:91]
	v_pk_mul_f32 v[8:9], v[8:9], v[94:95]
	v_pk_mul_f32 v[4:5], v[4:5], v[116:117]
	v_pk_mul_f32 v[2:3], v[2:3], v[114:115]
.LBB0_244:
	s_waitcnt vmcnt(5) lgkmcnt(0)
	s_barrier
	s_add_i32 s5, s20, 0
	v_add_u32_e32 v83, s5, v230
	v_add_u32_e32 v88, s5, v232
	ds_read_b128 v[84:87], v83 offset:49152
	ds_read_b128 v[186:189], v88 offset:57344
	v_add_u32_e32 v83, s5, v231
	v_add_u32_e32 v88, s5, v233
	ds_read_b128 v[190:193], v83 offset:49152
	ds_read_b128 v[210:213], v88 offset:57344
	s_waitcnt lgkmcnt(3)
	v_mfma_f32_32x32x16_bf16 v[114:129], v[84:87], v[130:133], v[66:81]
	v_add_u32_e32 v220, s5, v204
	v_add_u32_e32 v83, v220, v227
	ds_read_b128 v[236:239], v83 offset:49152
	v_lshl_add_u32 v234, s77, 13, v206
	v_add_u32_e32 v235, s13, v202
	v_exp_f32_e32 v244, v98
	ds_read_b128 v[240:243], v83 offset:57344
	v_add_f32_e32 v98, v244, v82
	s_waitcnt lgkmcnt(4)
	v_mfma_f32_32x32x16_bf16 v[82:97], v[186:189], v[130:133], v[66:81]
	v_exp_f32_e32 v245, v99
	s_waitcnt lgkmcnt(3)
	v_mfma_f32_32x32x16_bf16 v[114:129], v[190:193], v[134:137], v[114:129]
	v_add_u32_e32 v99, v220, v226
	ds_read_b128 v[186:189], v99 offset:49152
	v_add_f32_e32 v98, v245, v98
	v_exp_f32_e32 v246, v100
	s_waitcnt lgkmcnt(3)
	v_mfma_f32_32x32x16_bf16 v[82:97], v[210:213], v[134:137], v[82:97]
	ds_read_b128 v[190:193], v99 offset:57344
	v_add_f32_e32 v248, v246, v98
	v_exp_f32_e32 v247, v101
	s_waitcnt lgkmcnt(3)
	v_mfma_f32_32x32x16_bf16 v[114:129], v[236:239], v[138:141], v[114:129]
	v_add_u32_e32 v210, v220, v225
	ds_read_b128 v[98:101], v210 offset:49152
	v_exp_f32_e32 v249, v102
	v_add_f32_e32 v102, v247, v248
	s_waitcnt lgkmcnt(3)
	v_mfma_f32_32x32x16_bf16 v[82:97], v[240:243], v[138:141], v[82:97]
	ds_read_b128 v[210:213], v210 offset:57344
	v_add_f32_e32 v102, v249, v102
	v_exp_f32_e32 v248, v103
	s_waitcnt lgkmcnt(3)
	v_mfma_f32_32x32x16_bf16 v[114:129], v[186:189], v[142:145], v[114:129]
	v_add_u32_e32 v103, v220, v224
	ds_read_b128 v[236:239], v103 offset:49152
	v_add_f32_e32 v102, v248, v102
	v_exp_f32_e32 v240, v104
	s_waitcnt lgkmcnt(3)
	v_mfma_f32_32x32x16_bf16 v[82:97], v[190:193], v[142:145], v[82:97]
	ds_read_b128 v[186:189], v103 offset:57344
	v_add_f32_e32 v242, v240, v102
	v_exp_f32_e32 v241, v105
	s_waitcnt lgkmcnt(3)
	v_mfma_f32_32x32x16_bf16 v[114:129], v[98:101], v[154:157], v[114:129]
	v_add_u32_e32 v190, v220, v223
	ds_read_b128 v[102:105], v190 offset:49152
	v_add_f32_e32 v98, v241, v242
	v_exp_f32_e32 v243, v106
	s_waitcnt lgkmcnt(3)
	v_mfma_f32_32x32x16_bf16 v[82:97], v[210:213], v[154:157], v[82:97]
	ds_read_b128 v[190:193], v190 offset:57344
	v_add_f32_e32 v100, v243, v98
	v_exp_f32_e32 v242, v107
	v_cvt_pk_bf16_f32 v98, v244, v245
	v_cvt_pk_bf16_f32 v99, v246, v247
	s_waitcnt lgkmcnt(3)
	v_mfma_f32_32x32x16_bf16 v[114:129], v[236:239], v[150:153], v[114:129]
	v_add_u32_e32 v106, v220, v222
	ds_read_b128 v[210:213], v106 offset:49152
	v_add_f32_e32 v107, v242, v100
	v_exp_f32_e32 v220, v108
	v_cvt_pk_bf16_f32 v100, v249, v248
	v_cvt_pk_bf16_f32 v101, v240, v241
	s_waitcnt lgkmcnt(3)
	v_mfma_f32_32x32x16_bf16 v[82:97], v[186:189], v[150:153], v[82:97]
	ds_read_b128 v[236:239], v106 offset:57344
	v_add_f32_e32 v241, v220, v107
	v_permlane32_swap_b32_e32 v98, v100
	v_permlane32_swap_b32_e32 v99, v101
	v_exp_f32_e32 v240, v109
	s_waitcnt lgkmcnt(3)
	v_mfma_f32_32x32x16_bf16 v[114:129], v[102:105], v[146:149], v[114:129]
	v_add_u32_e32 v186, v234, v221
	ds_read_b128 v[106:109], v186
	v_exp_f32_e32 v244, v110
	v_add_f32_e32 v110, v240, v241
	s_waitcnt lgkmcnt(3)
	v_mfma_f32_32x32x16_bf16 v[82:97], v[190:193], v[146:149], v[82:97]
	ds_read_b128 v[102:105], v186 offset:4096
	v_add_f32_e32 v110, v244, v110
	v_exp_f32_e32 v241, v111
	s_waitcnt lgkmcnt(3)
	v_mfma_f32_32x32x16_bf16 v[114:129], v[210:213], v[158:161], v[114:129]
	v_add_u32_e32 v111, v234, v209
	ds_read_b128 v[186:189], v111
	v_add_f32_e32 v110, v241, v110
	v_exp_f32_e32 v245, v112
	s_waitcnt lgkmcnt(3)
	v_mfma_f32_32x32x16_bf16 v[82:97], v[236:239], v[158:161], v[82:97]
	ds_read_b128 v[190:193], v111 offset:4096
	v_add_f32_e32 v210, v245, v110
	v_exp_f32_e32 v246, v113
	s_waitcnt lgkmcnt(3)
	v_mfma_f32_32x32x16_bf16 v[114:129], v[106:109], v[162:165], v[114:129]
	v_add_u32_e32 v211, v234, v208
	ds_read_b128 v[110:113], v211
	v_add_f32_e32 v236, v246, v210
	s_waitcnt lgkmcnt(3)
	v_mfma_f32_32x32x16_bf16 v[82:97], v[102:105], v[162:165], v[82:97]
	ds_read_b128 v[106:109], v211 offset:4096
	v_cvt_pk_bf16_f32 v102, v243, v242
	v_cvt_pk_bf16_f32 v103, v220, v240
	s_waitcnt lgkmcnt(3)
	v_mfma_f32_32x32x16_bf16 v[114:129], v[186:189], v[166:169], v[114:129]
	v_add_u32_e32 v220, v234, v207
	ds_read_b128 v[210:213], v220
	v_cvt_pk_bf16_f32 v104, v244, v241
	v_cvt_pk_bf16_f32 v105, v245, v246
	s_waitcnt lgkmcnt(3)
	v_mfma_f32_32x32x16_bf16 v[82:97], v[190:193], v[166:169], v[82:97]
	ds_read_b128 v[186:189], v220 offset:4096
	v_permlane32_swap_b32_e32 v102, v104
	v_permlane32_swap_b32_e32 v103, v105
	s_waitcnt lgkmcnt(3)
	v_mfma_f32_32x32x16_bf16 v[114:129], v[110:113], v[170:173], v[114:129]
	v_mov_b32_e32 v110, v236
	s_nop 1
	v_permlane32_swap_b32_e32 v236, v110
	v_add_f32_e32 v110, v236, v110
	v_add_f32_e32 v234, v1, v110
	s_waitcnt lgkmcnt(2)
	v_mfma_f32_32x32x16_bf16 v[82:97], v[106:109], v[170:173], v[82:97]
	ds_read_b64_tr_b16 v[110:111], v235
	ds_read_b64_tr_b16 v[112:113], v235 offset:2048
	s_waitcnt lgkmcnt(3)
	v_mfma_f32_32x32x16_bf16 v[114:129], v[210:213], v[174:177], v[114:129]
	ds_read_b64_tr_b16 v[236:237], v235 offset:512
	ds_read_b64_tr_b16 v[238:239], v235 offset:2560
	s_waitcnt lgkmcnt(4)
	v_mfma_f32_32x32x16_bf16 v[82:97], v[186:189], v[174:177], v[82:97]
	ds_read_b64_tr_b16 v[106:107], v235 offset:1024
	ds_read_b64_tr_b16 v[108:109], v235 offset:3072
	s_waitcnt lgkmcnt(4)
	v_mfma_f32_32x32x16_bf16 v[50:65], v[182:185], v[110:113], v[50:65]
	s_cmpk_lt_u32 s78, 0x7c
	s_cselect_b64 s[6:7], -1, 0
	s_add_i32 s8, s13, s76
	ds_read_b64_tr_b16 v[190:191], v235 offset:1536
	ds_read_b64_tr_b16 v[192:193], v235 offset:3584
	s_add_u32 s12, s18, 0x15018100
	s_addc_u32 s13, s19, 0
	s_add_i32 s1, s1, s73
	s_mov_b32 m0, s1
	s_nop 0
	global_load_lds_dwordx4 v199, s[12:13]
	s_add_u32 s18, s18, 0x1501c100
	s_addc_u32 s19, s19, 0
	s_add_i32 s5, s1, 0x2000
	s_cmpk_gt_u32 s78, 0x7b
	s_waitcnt lgkmcnt(4)
	v_mfma_f32_32x32x16_bf16 v[34:49], v[182:185], v[236:239], v[34:49]
	ds_read_b64_tr_b16 v[186:187], v235 offset:4096
	ds_read_b64_tr_b16 v[188:189], v235 offset:6144
	s_mov_b32 m0, s5
	s_nop 0
	global_load_lds_dwordx4 v199, s[18:19]
	ds_read_b64_tr_b16 v[110:111], v235 offset:4608
	ds_read_b64_tr_b16 v[112:113], v235 offset:6656
	s_cbranch_scc1 .LBB0_246
	s_add_u32 s12, s14, 0x20000
	s_addc_u32 s13, s15, 0
	s_mov_b32 m0, s8
	s_nop 0
	global_load_lds_dwordx4 v197, s[12:13]
.LBB0_246:
	s_waitcnt lgkmcnt(6)
	v_mfma_f32_32x32x16_bf16 v[18:33], v[182:185], v[106:109], v[18:33]
	ds_read_b64_tr_b16 v[106:107], v235 offset:5120
	ds_read_b64_tr_b16 v[108:109], v235 offset:7168
	v_cndmask_b32_e64 v1, 0, 1, s[6:7]
	v_cmp_ne_u32_e64 s[42:43], 1, v1
	s_andn2_b64 vcc, exec, s[6:7]
	s_cbranch_vccnz .LBB0_248
	s_add_u32 s6, s14, 0x22000
	s_addc_u32 s7, s15, 0
	s_add_i32 s1, s8, 0x1000
	s_mov_b32 m0, s1
	s_nop 0
	global_load_lds_dwordx4 v197, s[6:7]

.LBB0_249:
	ds_read_b64_tr_b16 v[182:183], v235 offset:5632
	ds_read_b64_tr_b16 v[184:185], v235 offset:7680
	s_and_b64 vcc, exec, s[42:43]
	s_cbranch_vccnz .LBB0_251
	s_add_i32 s5, s0, s75
	s_add_u32 s0, s16, 0x8000
	s_addc_u32 s1, s17, 0
	s_mov_b32 m0, s5
	s_nop 0
	global_load_lds_dwordx4 v198, s[0:1]

; #define SBAR() __builtin_amdgcn_sched_barrier(0)
; __device__ __forceinline__ int v_rd_base(int lane) { return ((lane & 3) << 3) | (((lane >> 2) & 3) << 6) | (((lane >> 4) & 1) << 5) | (((lane >> 5) & 1) << 8); }
; #define DMA_K2(KB, RB, t, slot) do { const bf16_t* s_ = (KB) + (long)(t) * (KVBLK * LDK); const unsigned d_ = (unsigned)__builtin_amdgcn_readfirstlane(kn_dst + (slot) * SHM_KN); \
;     glds16s(s_, kn_off, d_); glds16s(s_ + 16 * LDK, kn_off, d_ + 4096); glds16s((RB) + (long)(t) * (KVBLK * 64), kr_off, (unsigned)__builtin_amdgcn_readfirstlane(kr_dst + (slot) * SHM_KR)); } while (0)
; #define DMA_V2(VB, t, slot) do { const bf16_t* s_ = (VB) + (long)(t) * (KVBLK * LDK); const unsigned d_ = (unsigned)__builtin_amdgcn_readfirstlane(v_dst + (slot) * SHM_V); \
;     glds16s(s_, v_off, d_); glds16s(s_ + 32 * LDK, v_off, d_ + 8192); } while (0)
; #define EXP16(P) do { _Pragma("unroll") for (int r = 0; r < 16; ++r) P[r] = __builtin_amdgcn_exp2f(P[r]); } while (0)
; #define PSWAP(A0, A1, B0, B1, OUT) do { auto r0_ = __builtin_amdgcn_permlane32_swap(A0, B0, false, false); auto r1_ = __builtin_amdgcn_permlane32_swap(A1, B1, false, false); \
;     u32x4 w_ = {r0_[0], r1_[0], r0_[1], r1_[1]}; OUT = __builtin_bit_cast(bf16x8, w_); } while (0)
; __device__ __forceinline__ void mla_unit(char* lds, const bf16_t* __restrict__ Qp, const bf16_t* __restrict__ Knp, const bf16_t* __restrict__ Vp, ...
;     ...
;   { EXP16(pB1); float s_ = sum0;
; #pragma unroll
;     for (int r = 0; r < 16; ++r) s_ += pB1[r];
;     auto rr_ = __builtin_amdgcn_permlane32_swap(__float_as_uint(s_), __float_as_uint(s_), false, false); l_reg += __uint_as_float(rr_[0]) + __uint_as_float(rr_[1]);
;     { unsigned a0_ = cvtpk(pB1[0], pB1[1]), a1_ = cvtpk(pB1[2], pB1[3]), b0_ = cvtpk(pB1[4], pB1[5]), b1_ = cvtpk(pB1[6], pB1[7]); PSWAP(a0_, a1_, b0_, b1_, pa2); }
;     { unsigned a0_ = cvtpk(pB1[8], pB1[9]), a1_ = cvtpk(pB1[10], pB1[11]), b0_ = cvtpk(pB1[12], pB1[13]), b1_ = cvtpk(pB1[14], pB1[15]); PSWAP(a0_, a1_, b0_, b1_, pa3); } }
;   SBAR();
;   pv_d0(o, (int)(lds0 + P_V) + v_rd_base(lane) + s0 * SHM_V, pa0, pa1, pa2, pa3);
;   asm volatile("s_waitcnt lgkmcnt(0)\n\ts_barrier" ::: "memory");
;   if (has_next) { DMA_K2(nKnp, nKrp, 0, 0); DMA_V2(nVp, 0, 0); DMA_K2(nKnp, nKrp, 1, 1); DMA_V2(nVp, 1, 1); DMA_K2(nKnp, nKrp, 2, 2); }
.LBB0_264:
	v_exp_f32_e32 v92, v66
	v_exp_f32_e32 v93, v67
	v_exp_f32_e32 v94, v68
	v_exp_f32_e32 v69, v69
	v_exp_f32_e32 v70, v70
	v_add_f32_e32 v66, v92, v91
	v_exp_f32_e32 v71, v71
	v_add_f32_e32 v66, v93, v66
	v_exp_f32_e32 v72, v72
	v_add_f32_e32 v66, v94, v66
	v_exp_f32_e32 v73, v73
	v_add_f32_e32 v66, v69, v66
	v_exp_f32_e32 v74, v74
	v_add_f32_e32 v66, v70, v66
	v_exp_f32_e32 v75, v75
	v_add_f32_e32 v66, v71, v66
	v_exp_f32_e32 v76, v76
	v_add_f32_e32 v66, v72, v66
	v_exp_f32_e32 v77, v77
	v_add_f32_e32 v66, v73, v66
	v_exp_f32_e32 v78, v78
	v_add_f32_e32 v66, v74, v66
	v_exp_f32_e32 v79, v79
	v_add_f32_e32 v66, v75, v66
	v_exp_f32_e32 v80, v80
	v_add_f32_e32 v66, v76, v66
	v_exp_f32_e32 v81, v81
	v_add_f32_e32 v66, v77, v66
	v_add_f32_e32 v66, v78, v66
	v_add_f32_e32 v66, v79, v66
	s_add_i32 s8, s74, s66
	v_add_f32_e32 v66, v80, v66
	s_cmpk_lt_i32 s8, 0x400
	s_waitcnt vmcnt(0) lgkmcnt(0)
	s_barrier
	v_add_f32_e32 v66, v81, v66
	s_cselect_b64 s[6:7], -1, 0
	s_cmpk_gt_i32 s8, 0x3ff
	v_mov_b32_e32 v67, v66
	s_cselect_b64 s[42:43], -1, 0
	s_nop 0
	v_permlane32_swap_b32_e32 v66, v67
	v_cvt_pk_bf16_f32 v68, v92, v93
	v_cvt_pk_bf16_f32 v69, v94, v69
	v_cvt_pk_bf16_f32 v70, v70, v71
	v_cvt_pk_bf16_f32 v71, v72, v73
	v_cvt_pk_bf16_f32 v72, v74, v75
	v_cvt_pk_bf16_f32 v73, v76, v77
	v_cvt_pk_bf16_f32 v74, v78, v79
	v_cvt_pk_bf16_f32 v75, v80, v81
	s_nop 0
	v_permlane32_swap_b32_e32 v68, v70
	v_permlane32_swap_b32_e32 v69, v71
	v_permlane32_swap_b32_e32 v72, v74
	v_permlane32_swap_b32_e32 v73, v75
	s_cmp_lg_u32 0, -1
	s_cselect_b32 s0, 0, 0
	s_addk_i32 s0, 0x4000
	v_add_u32_e32 v80, s0, v201
	ds_read_b64_tr_b16 v[76:77], v80 offset:0
	ds_read_b64_tr_b16 v[78:79], v80 offset:0x800
	ds_read_b64_tr_b16 v[92:93], v80 offset:0x1000
	ds_read_b64_tr_b16 v[94:95], v80 offset:0x1800
	ds_read_b64_tr_b16 v[96:97], v80 offset:0x2000
	ds_read_b64_tr_b16 v[98:99], v80 offset:0x2800
	ds_read_b64_tr_b16 v[100:101], v80 offset:0x3000
	ds_read_b64_tr_b16 v[102:103], v80 offset:0x3800
	s_waitcnt lgkmcnt(0)
	s_nop 0
	v_mfma_f32_32x32x16_bf16 v[50:65], v[82:85], v[76:79], v[50:65]
	ds_read_b64_tr_b16 v[76:77], v80 offset:0x200
	ds_read_b64_tr_b16 v[78:79], v80 offset:0xa00
	v_mfma_f32_32x32x16_bf16 v[50:65], v[86:89], v[92:95], v[50:65]
	ds_read_b64_tr_b16 v[92:93], v80 offset:0x1200
	ds_read_b64_tr_b16 v[94:95], v80 offset:0x1a00
	v_mfma_f32_32x32x16_bf16 v[50:65], v[68:71], v[96:99], v[50:65]
	ds_read_b64_tr_b16 v[96:97], v80 offset:0x2200
	ds_read_b64_tr_b16 v[98:99], v80 offset:0x2a00
	v_mfma_f32_32x32x16_bf16 v[50:65], v[72:75], v[100:103], v[50:65]
	ds_read_b64_tr_b16 v[100:101], v80 offset:0x3200
	ds_read_b64_tr_b16 v[102:103], v80 offset:0x3a00
	s_waitcnt lgkmcnt(0)
	v_mfma_f32_32x32x16_bf16 v[34:49], v[82:85], v[76:79], v[34:49]
	ds_read_b64_tr_b16 v[76:77], v80 offset:0x400
	ds_read_b64_tr_b16 v[78:79], v80 offset:0xc00
	v_mfma_f32_32x32x16_bf16 v[34:49], v[86:89], v[92:95], v[34:49]
	ds_read_b64_tr_b16 v[92:93], v80 offset:0x1400
	ds_read_b64_tr_b16 v[94:95], v80 offset:0x1c00
	v_mfma_f32_32x32x16_bf16 v[34:49], v[68:71], v[96:99], v[34:49]
	ds_read_b64_tr_b16 v[96:97], v80 offset:0x2400
	ds_read_b64_tr_b16 v[98:99], v80 offset:0x2c00
	v_mfma_f32_32x32x16_bf16 v[34:49], v[72:75], v[100:103], v[34:49]
	ds_read_b64_tr_b16 v[100:101], v80 offset:0x3400
	ds_read_b64_tr_b16 v[102:103], v80 offset:0x3c00
	s_waitcnt lgkmcnt(0)
	v_mfma_f32_32x32x16_bf16 v[18:33], v[82:85], v[76:79], v[18:33]
	ds_read_b64_tr_b16 v[76:77], v80 offset:0x600
	ds_read_b64_tr_b16 v[78:79], v80 offset:0xe00
	v_mfma_f32_32x32x16_bf16 v[18:33], v[86:89], v[92:95], v[18:33]
	ds_read_b64_tr_b16 v[92:93], v80 offset:0x1600
	ds_read_b64_tr_b16 v[94:95], v80 offset:0x1e00
	v_mfma_f32_32x32x16_bf16 v[18:33], v[68:71], v[96:99], v[18:33]
	ds_read_b64_tr_b16 v[96:97], v80 offset:0x2600
	ds_read_b64_tr_b16 v[98:99], v80 offset:0x2e00
	v_mfma_f32_32x32x16_bf16 v[18:33], v[72:75], v[100:103], v[18:33]
	ds_read_b64_tr_b16 v[100:101], v80 offset:0x3600
	ds_read_b64_tr_b16 v[102:103], v80 offset:0x3e00
	s_waitcnt lgkmcnt(0)
	v_mfma_f32_32x32x16_bf16 v[2:17], v[82:85], v[76:79], v[2:17]
	s_waitcnt lgkmcnt(0)
	s_barrier
	s_and_b64 vcc, exec, s[42:43]
	v_mfma_f32_32x32x16_bf16 v[2:17], v[86:89], v[92:95], v[2:17]
	v_mfma_f32_32x32x16_bf16 v[2:17], v[68:71], v[96:99], v[2:17]
	v_mfma_f32_32x32x16_bf16 v[2:17], v[72:75], v[100:103], v[2:17]
	s_cbranch_vccnz .LBB0_266
	s_and_b64 s[0:1], s[6:7], exec
	s_cselect_b32 s5, s8, s74
	s_ashr_i32 s0, s5, 9
	s_lshl_b32 s5, s5, 18
	s_ashr_i32 s1, s0, 31
	s_and_b32 s5, s5, 0x7800000
	v_readlane_b32 s6, v254, 62
	s_add_u32 s5, s6, s5
	v_readlane_b32 s6, v254, 63
	s_addc_u32 s9, s6, 0
	s_lshl_b64 s[6:7], s[0:1], 22
	s_add_u32 s6, s5, s6
	s_addc_u32 s7, s9, s7
	s_add_u32 s12, s6, 0x100
	s_addc_u32 s13, s7, 0
	s_lshl_b64 s[0:1], s[0:1], 20
	s_add_u32 s0, s26, s0
	s_addc_u32 s1, s27, s1
	s_mov_b32 m0, s76
	s_nop 0
	global_load_lds_dwordx4 v197, s[6:7]
	s_add_u32 s14, s6, 0x2000
	s_addc_u32 s15, s7, 0
	s_add_i32 s5, s76, 0x1000
	s_mov_b32 m0, s5
	s_nop 0
	global_load_lds_dwordx4 v197, s[14:15]
	s_mov_b32 m0, s75
	s_nop 0
	global_load_lds_dwordx4 v198, s[0:1]
	s_nop 0
	s_mov_b32 m0, s73
	s_nop 0
	global_load_lds_dwordx4 v199, s[12:13]
	s_add_u32 s12, s6, 0x4100
	s_addc_u32 s13, s7, 0
	s_add_i32 s5, s73, 0x2000
	s_mov_b32 m0, s5
	s_nop 0
	global_load_lds_dwordx4 v199, s[12:13]
	s_add_u32 s12, s6, 0x8000
	s_addc_u32 s13, s7, 0
	s_cmp_lg_u32 0, -1
	s_cselect_b32 s5, 0, 0
	s_add_i32 s9, s5, s72
	s_add_i32 s14, s9, 0x10000
	s_mov_b32 m0, s14
	s_nop 0
	global_load_lds_dwordx4 v197, s[12:13]
	s_add_u32 s12, s6, 0xa000
	s_addc_u32 s13, s7, 0
	s_add_i32 s14, s9, 0x11000
	s_mov_b32 m0, s14
	s_nop 0
	global_load_lds_dwordx4 v197, s[12:13]
	s_add_u32 s12, s0, 0x2000
	s_addc_u32 s13, s1, 0
	s_add_i32 s5, s5, s71
	s_add_i32 s14, s5, 0x1a000
	s_mov_b32 m0, s14
	s_nop 0
	global_load_lds_dwordx4 v198, s[12:13]
	s_add_u32 s12, s6, 0x8100
	s_addc_u32 s13, s7, 0
	s_add_i32 s14, s5, 0x4000
	s_mov_b32 m0, s14
	s_nop 0
	global_load_lds_dwordx4 v199, s[12:13]
	s_add_u32 s12, s6, 0xc100
	s_addc_u32 s13, s7, 0
	s_add_i32 s14, s5, 0x6000
	s_mov_b32 m0, s14
	s_nop 0
	global_load_lds_dwordx4 v199, s[12:13]
	s_add_u32 s12, s6, 0x10000
	s_addc_u32 s13, s7, 0
	s_add_i32 s14, s9, 0x14000
	s_add_u32 s6, s6, 0x12000
	s_mov_b32 m0, s14
	s_nop 0
	global_load_lds_dwordx4 v197, s[12:13]
	s_addc_u32 s7, s7, 0
	s_add_i32 s9, s9, 0x15000
	s_mov_b32 m0, s9
	s_nop 0
	global_load_lds_dwordx4 v197, s[6:7]
	s_add_u32 s0, s0, 0x4000
	s_addc_u32 s1, s1, 0
	s_add_i32 s5, s5, 0x1c000
	s_mov_b32 m0, s5
	s_nop 0
	global_load_lds_dwordx4 v198, s[0:1]

; __device__ __forceinline__ int opaque_tid() { int t = threadIdx.x; asm volatile("" : "+v"(t)); return t; }
; __device__ __forceinline__ float bf2f(unsigned h) { return __uint_as_float(h << 16); }
; __device__ __forceinline__ void na_unit3(char* lds, const bf16_t* __restrict__ Qp, const bf16_t* __restrict__ Knp, const bf16_t* __restrict__ Vp, ...
;     ...
;   const int tid = opaque_tid(), wid = __builtin_amdgcn_readfirstlane(tid >> 6), lane = tid & 63, r32 = lane & 31, hi = lane >> 5;
;   float* wsf = (float*)(lds + N_WS) + wid * 64; float* li_l = wsf; float* al_l = wsf + 32;
;   float* tab = (float*)(lds + N_TAB) + 256;
;   const unsigned lds0 = (unsigned)(uintptr_t)lds;
;   const int pk = (wid & 3) + 8 * (wid >> 2);
;   const int krow_n = 4 * pk + (lane >> 4);
;   const unsigned kn_off = (unsigned)(krow_n * LDK + (((lane & 15) ^ (krow_n & 15)) << 3)) * 2u;
;   const int vst_ = 2 * wid + (lane >> 5), vkk = (vst_ >> 2) * 8 + ((lane >> 2) & 7), vkey = (vkk & ~0xC) | ((vkk & 4) << 1) | ((vkk & 8) >> 1), vcol = (vst_ & 3) * 32 + (lane & 3) * 8;
;   const unsigned v_off = (unsigned)(vkey * LDK + vcol) * 2u;
;   const unsigned kn_dst = lds0 + N_KN + pk * 1024, v_dst = lds0 + N_V + wid * 1024;
;     ...
;   DMA_T(0, 0); DMA_T(1, 1); DMA_T(2, 2);
;   float l_reg = 0.f; f32x16 o[4] = {}; bf16x8 qr[8];
;   const bf16_t* Qw = Qp + (long)(wid * QBLK + r32) * LDQ + hi * 8;
; #pragma unroll
;   for (int d0 = 0; d0 < 8; ++d0) { const u32x4 raw = *reinterpret_cast<const u32x4*>(Qw + d0 * 16); u32x4 w;
; #pragma unroll
;     for (int p = 0; p < 4; ++p) w[p] = cvtpk(bf2f(raw[p] & 0xffffu) * C, bf2f(raw[p] >> 16) * C);
;     qr[d0] = *reinterpret_cast<bf16x8*>(&w); }
; __global__ void __launch_bounds__(NWAVES * 64, 2) fwd_mega(Args args) {
;     ...
;                 const int bh = u >> 5, rg = u & 31, b = bh >> 4, h = bh & 15, r0row = rg * 4;
;                 const int R0 = min(max(r0row - 4, 0), 120), last = min(max(r0row - 1, 0), 120) + 7, NT = last - R0 + 1;
;                 const size_t tok0 = (size_t)b * SEQ + r0row * 64, key0 = (size_t)b * SEQ + R0 * 64;
;                 const size_t TS = (size_t)M_TOK * 256; const bf16_t* hb = QKVZ + (size_t)(h >> 1) * TS + (h & 1) * 128;
;                 att::na_unit3((char*)lds, hb + tok0 * 256, hb + 8 * TS + key0 * 256, hb + 16 * TS + key0 * 256,
.LBB0_276:
	s_lshl_b32 s1, s76, 2
	s_ashr_i32 s30, s76, 9
	s_and_b32 s1, s1, 0x7c
	v_sub_u32_e64 v1, s1, 4 clamp
	s_ashr_i32 s31, s30, 31
	v_readfirstlane_b32 s85, v1
	s_lshl_b64 s[8:9], s[30:31], 13
	s_lshl_b32 s5, s1, 6
	s_or_b32 s34, s8, s5
	s_lshl_b32 s5, s85, 6
	s_or_b32 s8, s8, s5
	s_lshl_b32 s5, s76, 17
	s_lshr_b32 s0, s76, 5
	s_bfe_u32 s77, s76, 0x40005
	s_and_b32 s5, s5, 0x3800000
	s_add_u32 s5, s90, s5
	s_addc_u32 s6, s91, 0
	s_lshl_b32 s7, s76, 3
	s_and_b32 s7, s7, 0x100
	s_mov_b32 s35, s9
	s_add_u32 s81, s5, s7
	s_addc_u32 s84, s6, 0
	s_lshl_b64 s[6:7], s[34:35], 9
	s_add_u32 s6, s81, s6
	s_addc_u32 s7, s84, s7
	s_lshl_b64 s[8:9], s[8:9], 9
	s_add_u32 s5, s81, s8
	s_addc_u32 s14, s84, s9
	s_add_u32 s64, s5, 0x4000000
	s_addc_u32 s65, s14, 0
	v_mov_b32_e32 v2, v252
	s_add_u32 s78, s5, 0x8000000
	s_addc_u32 s79, s14, 0
	v_readfirstlane_b32 s10, v2
	s_ashr_i32 s15, s10, 6
	s_ashr_i32 s9, s10, 5
	s_and_b32 s8, s15, 3
	s_and_b32 s9, s9, -8
	s_or_b32 s8, s8, s9
	s_lshl_b32 s9, s8, 2
	v_bfe_u32 v1, v2, 4, 2
	v_or_b32_e32 v3, s9, v1
	v_bitop3_b32 v1, s9, v2, v1 bitop3:0x36
	s_ashr_i32 s12, s10, 4
	v_lshlrev_b32_e32 v3, 9, v3
	v_lshlrev_b32_e32 v1, 4, v1
	s_and_b32 s13, s12, 0x7ffff0
	s_lshr_b32 s12, s12, 1
	v_and_or_b32 v223, v1, s53, v3
	s_lshl_b32 s9, s15, 1
	v_lshrrev_b32_e32 v1, 2, v2
	v_lshrrev_b32_e32 v3, 1, v2
	s_and_b32 s12, s12, 4
	s_lshl_b32 s8, s8, 10
	v_bfe_u32 v222, v2, 5, 1
	v_and_or_b32 v1, v1, 3, s13
	v_and_b32_e32 v3, 8, v3
	s_cmp_lg_u32 0, -1
	v_or3_b32 v1, v1, v3, s12
	v_and_or_b32 v3, s9, 2, v222
	s_cselect_b32 s9, 0, 0
	s_add_i32 s16, s9, s8
	s_lshl_b32 s89, s15, 10
	v_lshlrev_b32_e32 v18, 4, v2
	s_add_i32 s88, s16, 0x10000
	s_add_i32 s89, s89, s9
	s_mov_b32 m0, s88
	s_nop 0
	global_load_lds_dwordx4 v223, s[64:65]
	v_and_b32_e32 v4, 48, v18
	s_add_u32 s8, s5, 0x4002000
	v_lshl_or_b32 v3, v3, 6, v4
	s_addc_u32 s9, s14, 0
	s_add_i32 s12, s88, 0x1000
	s_mov_b32 m0, s12
	s_nop 0
	global_load_lds_dwordx4 v223, s[8:9]
	v_lshl_or_b32 v224, v1, 9, v3
	s_mov_b32 m0, s89
	s_nop 0
	global_load_lds_dwordx4 v224, s[78:79]
	s_add_u32 s8, s5, 0x8004000
	s_addc_u32 s9, s14, 0
	s_add_i32 s12, s89, 0x2000
	s_mov_b32 m0, s12
	s_nop 0
	global_load_lds_dwordx4 v224, s[8:9]
	s_add_u32 s8, s5, 0x4008000
	s_addc_u32 s9, s14, 0
	s_add_u32 s12, s5, 0x8008000
	s_addc_u32 s13, s14, 0
	s_add_i32 s17, s16, 0x14000
	s_add_i32 s18, s89, 0x4000
	s_mov_b32 m0, s17
	s_nop 0
	global_load_lds_dwordx4 v223, s[8:9]
	s_add_u32 s8, s5, 0x400a000
	s_addc_u32 s9, s14, 0
	s_add_i32 s17, s16, 0x15000
	s_mov_b32 m0, s17
	s_nop 0
	global_load_lds_dwordx4 v223, s[8:9]
	s_mov_b32 m0, s18
	s_nop 0
	global_load_lds_dwordx4 v224, s[12:13]
	s_add_u32 s8, s5, 0x800c000
	s_addc_u32 s9, s14, 0
	s_add_i32 s12, s89, 0x6000
	s_mov_b32 m0, s12
	s_nop 0
	global_load_lds_dwordx4 v224, s[8:9]
	s_add_u32 s8, s5, 0x4010000
	s_addc_u32 s9, s14, 0
	s_add_u32 s12, s5, 0x8010000
	s_addc_u32 s13, s14, 0
	s_add_i32 s17, s16, 0x18000
	s_add_i32 s18, s89, 0x8000
	s_mov_b32 m0, s17
	s_nop 0
	global_load_lds_dwordx4 v223, s[8:9]
	s_add_u32 s8, s5, 0x4012000
	s_addc_u32 s9, s14, 0
	s_add_i32 s16, s16, 0x19000
	s_mov_b32 m0, s16
	s_nop 0
	global_load_lds_dwordx4 v223, s[8:9]
	s_mov_b32 m0, s18
	s_nop 0
	global_load_lds_dwordx4 v224, s[12:13]
	s_add_u32 s8, s5, 0x8014000
	v_and_b32_e32 v221, 31, v2
	s_addc_u32 s9, s14, 0
	s_lshl_b32 s80, s15, 5
	v_or_b32_e32 v4, s80, v221
	v_ashrrev_i32_e32 v5, 31, v4
	v_lshlrev_b64 v[4:5], 9, v[4:5]
	v_lshl_add_u64 v[4:5], s[6:7], 0, v[4:5]
	v_lshlrev_b32_e32 v204, 4, v222
	v_mov_b32_e32 v205, v0
	s_add_i32 s5, s89, 0xa000
	s_mov_b32 m0, s5
	s_nop 0
	global_load_lds_dwordx4 v224, s[8:9]
	v_lshl_add_u64 v[8:9], v[4:5], 0, v[204:205]
	global_load_dwordx4 v[160:163], v[8:9], off
	global_load_dwordx4 v[164:167], v[8:9], off offset:32
	global_load_dwordx4 v[168:171], v[8:9], off offset:64
	global_load_dwordx4 v[172:175], v[8:9], off offset:96
	global_load_dwordx4 v[176:179], v[8:9], off offset:128
	global_load_dwordx4 v[180:183], v[8:9], off offset:160
	global_load_dwordx4 v[184:187], v[8:9], off offset:192
	global_load_dwordx4 v[188:191], v[8:9], off offset:224
	s_movk_i32 s5, 0x1d1
	v_cmp_gt_i32_e32 vcc, s5, v2
	s_waitcnt vmcnt(7)
	v_lshlrev_b32_e32 v1, 16, v160
	v_and_b32_e32 v3, 0xffff0000, v160
	v_mul_f32_e32 v1, 0x3e0293ee, v1
	v_mul_f32_e32 v3, 0x3e0293ee, v3
	v_cvt_pk_bf16_f32 v160, v1, v3
	v_and_b32_e32 v1, 0xffff0000, v162
	v_lshlrev_b32_e32 v4, 16, v161
	v_and_b32_e32 v5, 0xffff0000, v161
	v_lshlrev_b32_e32 v10, 16, v162
	v_mul_f32_e32 v1, 0x3e0293ee, v1
	v_mul_f32_e32 v4, 0x3e0293ee, v4
	v_mul_f32_e32 v5, 0x3e0293ee, v5
	v_mul_f32_e32 v10, 0x3e0293ee, v10
	v_cvt_pk_bf16_f32 v161, v4, v5
	v_cvt_pk_bf16_f32 v162, v10, v1
	v_lshlrev_b32_e32 v1, 16, v163
	v_and_b32_e32 v3, 0xffff0000, v163
	v_mul_f32_e32 v1, 0x3e0293ee, v1
	v_mul_f32_e32 v3, 0x3e0293ee, v3
	v_cvt_pk_bf16_f32 v163, v1, v3
	s_waitcnt vmcnt(6)
	v_lshlrev_b32_e32 v1, 16, v164
	v_and_b32_e32 v3, 0xffff0000, v164
	v_lshlrev_b32_e32 v4, 16, v165
	v_and_b32_e32 v5, 0xffff0000, v165
	v_lshlrev_b32_e32 v10, 16, v166
	v_and_b32_e32 v6, 0xffff0000, v166
	v_lshlrev_b32_e32 v11, 16, v167
	v_and_b32_e32 v7, 0xffff0000, v167
	v_mul_f32_e32 v4, 0x3e0293ee, v4
	v_mul_f32_e32 v5, 0x3e0293ee, v5
	v_mul_f32_e32 v6, 0x3e0293ee, v6
	v_mul_f32_e32 v7, 0x3e0293ee, v7
	v_mul_f32_e32 v1, 0x3e0293ee, v1
	v_mul_f32_e32 v3, 0x3e0293ee, v3
	v_mul_f32_e32 v10, 0x3e0293ee, v10
	v_mul_f32_e32 v11, 0x3e0293ee, v11
	v_cvt_pk_bf16_f32 v164, v1, v3
	v_cvt_pk_bf16_f32 v165, v4, v5
	v_cvt_pk_bf16_f32 v166, v10, v6
	v_cvt_pk_bf16_f32 v167, v11, v7
	s_waitcnt vmcnt(5)
; __device__ __forceinline__ float bf2f(unsigned h) { return __uint_as_float(h << 16); }
; __device__ __forceinline__ void na_unit3(char* lds, const bf16_t* __restrict__ Qp, const bf16_t* __restrict__ Knp, const bf16_t* __restrict__ Vp, ...
;     ...
;   for (int d0 = 0; d0 < 8; ++d0) { const u32x4 raw = *reinterpret_cast<const u32x4*>(Qw + d0 * 16); u32x4 w;
; #pragma unroll
;     for (int p = 0; p < 4; ++p) w[p] = cvtpk(bf2f(raw[p] & 0xffffu) * C, bf2f(raw[p] >> 16) * C);
;     qr[d0] = *reinterpret_cast<bf16x8*>(&w); }
;   for (int i = tid; i < 15 * 31; i += NW * 64) tab[i] = rpb_h[i] * 1.4426950408889634f;
	v_lshlrev_b32_e32 v1, 16, v168
	v_and_b32_e32 v3, 0xffff0000, v168
	v_lshlrev_b32_e32 v4, 16, v169
	v_and_b32_e32 v5, 0xffff0000, v169
	v_lshlrev_b32_e32 v10, 16, v170
	v_and_b32_e32 v6, 0xffff0000, v170
	v_lshlrev_b32_e32 v11, 16, v171
	v_and_b32_e32 v7, 0xffff0000, v171
	v_mul_f32_e32 v4, 0x3e0293ee, v4
	v_mul_f32_e32 v5, 0x3e0293ee, v5
	v_mul_f32_e32 v6, 0x3e0293ee, v6
	v_mul_f32_e32 v7, 0x3e0293ee, v7
	v_mul_f32_e32 v1, 0x3e0293ee, v1
	v_mul_f32_e32 v3, 0x3e0293ee, v3
	v_mul_f32_e32 v10, 0x3e0293ee, v10
	v_mul_f32_e32 v11, 0x3e0293ee, v11
	v_cvt_pk_bf16_f32 v168, v1, v3
	v_cvt_pk_bf16_f32 v169, v4, v5
	v_cvt_pk_bf16_f32 v170, v10, v6
	v_cvt_pk_bf16_f32 v171, v11, v7
	s_waitcnt vmcnt(4)
	v_lshlrev_b32_e32 v1, 16, v172
	v_and_b32_e32 v3, 0xffff0000, v172
	v_lshlrev_b32_e32 v4, 16, v173
	v_and_b32_e32 v5, 0xffff0000, v173
	v_lshlrev_b32_e32 v10, 16, v174
	v_and_b32_e32 v6, 0xffff0000, v174
	v_lshlrev_b32_e32 v11, 16, v175
	v_and_b32_e32 v7, 0xffff0000, v175
	v_mul_f32_e32 v4, 0x3e0293ee, v4
	v_mul_f32_e32 v5, 0x3e0293ee, v5
	v_mul_f32_e32 v6, 0x3e0293ee, v6
	v_mul_f32_e32 v7, 0x3e0293ee, v7
	v_mul_f32_e32 v1, 0x3e0293ee, v1
	v_mul_f32_e32 v3, 0x3e0293ee, v3
	v_mul_f32_e32 v10, 0x3e0293ee, v10
	v_mul_f32_e32 v11, 0x3e0293ee, v11
	v_cvt_pk_bf16_f32 v172, v1, v3
	v_cvt_pk_bf16_f32 v173, v4, v5
	v_cvt_pk_bf16_f32 v174, v10, v6
	v_cvt_pk_bf16_f32 v175, v11, v7
	s_waitcnt vmcnt(3)
	v_lshlrev_b32_e32 v1, 16, v176
	v_and_b32_e32 v3, 0xffff0000, v176
	v_lshlrev_b32_e32 v4, 16, v177
	v_and_b32_e32 v5, 0xffff0000, v177
	v_lshlrev_b32_e32 v10, 16, v178
	v_and_b32_e32 v6, 0xffff0000, v178
	v_lshlrev_b32_e32 v11, 16, v179
	v_and_b32_e32 v7, 0xffff0000, v179
	v_mul_f32_e32 v4, 0x3e0293ee, v4
	v_mul_f32_e32 v5, 0x3e0293ee, v5
	v_mul_f32_e32 v6, 0x3e0293ee, v6
	v_mul_f32_e32 v7, 0x3e0293ee, v7
	v_mul_f32_e32 v1, 0x3e0293ee, v1
	v_mul_f32_e32 v3, 0x3e0293ee, v3
	v_mul_f32_e32 v10, 0x3e0293ee, v10
	v_mul_f32_e32 v11, 0x3e0293ee, v11
	v_cvt_pk_bf16_f32 v176, v1, v3
	v_cvt_pk_bf16_f32 v177, v4, v5
	v_cvt_pk_bf16_f32 v178, v10, v6
	v_cvt_pk_bf16_f32 v179, v11, v7
	s_waitcnt vmcnt(2)
	v_lshlrev_b32_e32 v1, 16, v180
	v_and_b32_e32 v3, 0xffff0000, v180
	v_lshlrev_b32_e32 v4, 16, v181
	v_and_b32_e32 v5, 0xffff0000, v181
	v_lshlrev_b32_e32 v10, 16, v182
	v_and_b32_e32 v6, 0xffff0000, v182
	v_lshlrev_b32_e32 v11, 16, v183
	v_and_b32_e32 v7, 0xffff0000, v183
	v_mul_f32_e32 v4, 0x3e0293ee, v4
	v_mul_f32_e32 v5, 0x3e0293ee, v5
	v_mul_f32_e32 v6, 0x3e0293ee, v6
	v_mul_f32_e32 v7, 0x3e0293ee, v7
	v_mul_f32_e32 v1, 0x3e0293ee, v1
	v_mul_f32_e32 v3, 0x3e0293ee, v3
	v_mul_f32_e32 v10, 0x3e0293ee, v10
	v_mul_f32_e32 v11, 0x3e0293ee, v11
	v_cvt_pk_bf16_f32 v180, v1, v3
	v_cvt_pk_bf16_f32 v181, v4, v5
	v_cvt_pk_bf16_f32 v182, v10, v6
	v_cvt_pk_bf16_f32 v183, v11, v7
	s_waitcnt vmcnt(1)
	v_lshlrev_b32_e32 v1, 16, v184
	v_and_b32_e32 v3, 0xffff0000, v184
	v_lshlrev_b32_e32 v4, 16, v185
	v_and_b32_e32 v5, 0xffff0000, v185
	v_lshlrev_b32_e32 v10, 16, v186
	v_and_b32_e32 v6, 0xffff0000, v186
	v_lshlrev_b32_e32 v11, 16, v187
	v_and_b32_e32 v7, 0xffff0000, v187
	v_mul_f32_e32 v4, 0x3e0293ee, v4
	v_mul_f32_e32 v5, 0x3e0293ee, v5
	v_mul_f32_e32 v6, 0x3e0293ee, v6
	v_mul_f32_e32 v7, 0x3e0293ee, v7
	v_mul_f32_e32 v1, 0x3e0293ee, v1
	v_mul_f32_e32 v3, 0x3e0293ee, v3
	v_mul_f32_e32 v10, 0x3e0293ee, v10
	v_mul_f32_e32 v11, 0x3e0293ee, v11
	v_cvt_pk_bf16_f32 v184, v1, v3
	v_cvt_pk_bf16_f32 v185, v4, v5
	v_cvt_pk_bf16_f32 v186, v10, v6
	v_cvt_pk_bf16_f32 v187, v11, v7
	s_waitcnt vmcnt(0)
	v_lshlrev_b32_e32 v1, 16, v188
	v_and_b32_e32 v3, 0xffff0000, v188
	v_lshlrev_b32_e32 v4, 16, v189
	v_and_b32_e32 v5, 0xffff0000, v189
	v_lshlrev_b32_e32 v8, 16, v190
	v_and_b32_e32 v6, 0xffff0000, v190
	v_lshlrev_b32_e32 v9, 16, v191
	v_and_b32_e32 v7, 0xffff0000, v191
	v_mul_f32_e32 v1, 0x3e0293ee, v1
	v_mul_f32_e32 v3, 0x3e0293ee, v3
	v_mul_f32_e32 v4, 0x3e0293ee, v4
	v_mul_f32_e32 v5, 0x3e0293ee, v5
	v_mul_f32_e32 v8, 0x3e0293ee, v8
	v_mul_f32_e32 v6, 0x3e0293ee, v6
	v_mul_f32_e32 v9, 0x3e0293ee, v9
	v_mul_f32_e32 v7, 0x3e0293ee, v7
	v_cvt_pk_bf16_f32 v188, v1, v3
	v_cvt_pk_bf16_f32 v189, v4, v5
	v_cvt_pk_bf16_f32 v190, v8, v6
	v_cvt_pk_bf16_f32 v191, v9, v7
	s_and_saveexec_b64 s[6:7], vcc
	s_cbranch_execz .LBB0_284
	v_max_i32_e32 v1, 0xffffffd1, v2
	v_sub_u32_e32 v1, v1, v2
	v_add_u32_e32 v1, 0x1ff, v1
	s_movk_i32 s5, 0x1ff
	v_cmp_lt_u32_e32 vcc, s5, v1
	s_mov_b64 s[26:27], -1
	v_mov_b32_e32 v4, v2
	s_and_saveexec_b64 s[8:9], vcc
	s_cbranch_execz .LBB0_281
	v_lshrrev_b32_e32 v1, 9, v1
	s_or_b32 s5, s77, s20
	v_readlane_b32 s12, v255, 0
	v_add_u32_e32 v1, 1, v1
	s_mulk_i32 s5, 0x744
	v_readlane_b32 s14, v255, 2
	v_readlane_b32 s15, v255, 3
	s_add_u32 s26, s14, s5
	v_and_b32_e32 v6, 0xfffffe, v1
	v_add_u32_e32 v3, 0x200, v2
	v_readlane_b32 s5, v254, 27
	s_addc_u32 s27, s15, 0
	s_mov_b64 s[36:37], 0
	v_lshl_add_u32 v7, v2, 2, s5
	v_mov_b32_e32 v8, v6
	v_mov_b64_e32 v[4:5], v[2:3]
	v_readlane_b32 s13, v255, 1
	v_readlane_b32 s16, v255, 4
	v_readlane_b32 s17, v255, 5
	v_readlane_b32 s18, v255, 6
	v_readlane_b32 s19, v255, 7

.LBB0_297:
	s_add_i32 s0, s69, -1
	s_cmp_le_i32 s0, s98
	s_cselect_b64 s[38:39], -1, 0
	s_cmp_gt_i32 s0, s98
	s_cbranch_scc1 .LBB0_299
	s_add_u32 s0, s86, 0xfbff8000
	s_addc_u32 s1, s87, -1
	s_add_u32 s6, s86, 0xffff8000
	s_addc_u32 s7, s87, -1
	s_lshl_b32 s5, s72, 14
	s_add_i32 s8, s5, s88
	s_add_i32 s5, s5, s89
	s_mov_b32 m0, s8
	s_nop 0
	global_load_lds_dwordx4 v223, s[0:1]
	s_add_u32 s0, s86, 0xfbffa000
	s_addc_u32 s1, s87, -1
	s_addk_i32 s8, 0x1000
	s_mov_b32 m0, s8
	s_nop 0
	global_load_lds_dwordx4 v223, s[0:1]
	s_mov_b32 m0, s5
	s_nop 0
	global_load_lds_dwordx4 v224, s[6:7]
	s_add_u32 s0, s86, 0xffffc000
	s_addc_u32 s1, s87, -1
	s_addk_i32 s5, 0x2000
	s_mov_b32 m0, s5
	s_nop 0
	global_load_lds_dwordx4 v224, s[0:1]

.LBB0_308:
	s_add_u32 s8, s86, 0xfc000000
	s_addc_u32 s9, s87, -1
	s_lshl_b32 s1, s72, 14
	s_addk_i32 s1, 0x4000
	s_and_b32 s1, s1, 0xc000
	s_add_i32 s5, s1, s88
	s_add_i32 s1, s1, s89
	s_mov_b32 m0, s5
	s_nop 0
	global_load_lds_dwordx4 v223, s[8:9]
	s_add_u32 s8, s86, 0xfc002000
	s_addc_u32 s9, s87, -1
	s_addk_i32 s5, 0x1000
	s_mov_b32 m0, s5
	s_nop 0
	global_load_lds_dwordx4 v223, s[8:9]
	s_mov_b32 m0, s1
	s_nop 0
	global_load_lds_dwordx4 v224, s[86:87]
	s_add_u32 s8, s86, 0x4000
	s_addc_u32 s9, s87, 0
	s_addk_i32 s1, 0x2000
	s_mov_b32 m0, s1
	s_nop 0
	global_load_lds_dwordx4 v224, s[8:9]

.LBB0_339:
	s_lshl_b64 s[6:7], s[10:11], 15
	s_add_u32 s8, s64, s6
	s_addc_u32 s9, s65, s7
	s_add_u32 s6, s78, s6
	s_addc_u32 s7, s79, s7
	s_add_i32 s5, s1, s88
	s_add_i32 s1, s1, s89
	s_mov_b32 m0, s5
	s_nop 0
	global_load_lds_dwordx4 v223, s[8:9]
	s_add_u32 s8, s8, 0x2000
	s_addc_u32 s9, s9, 0
	s_addk_i32 s5, 0x1000
	s_mov_b32 m0, s5
	s_nop 0
	global_load_lds_dwordx4 v223, s[8:9]
	s_mov_b32 m0, s1
	s_nop 0
	global_load_lds_dwordx4 v224, s[6:7]
	s_add_u32 s6, s6, 0x4000
	s_addc_u32 s7, s7, 0
	s_addk_i32 s1, 0x2000
	s_mov_b32 m0, s1
	s_nop 0
	global_load_lds_dwordx4 v224, s[6:7]
